# P5: the epilogue's row-statistics loads issued at unit start into spare registers; epilogue copies them instead of loading and waiting
# speedup vs baseline: 1.0033x; 1.0033x over previous
.Lnr_p5:
	s_lshl_b32 s98, s33, 11
	s_add_u32 s98, s14, s98
	s_addc_u32 s99, s15, 0
	v_lshl_add_u64 v[100:101], s[98:99], 0, v[80:81]
	global_load_dwordx2 v[84:85], v[100:101], off
	global_load_dwordx2 v[86:87], v[100:101], off offset:128
	global_load_dwordx2 v[88:89], v[100:101], off offset:256
	global_load_dwordx2 v[90:91], v[100:101], off offset:384
	global_load_dwordx2 v[92:93], v[100:101], off offset:1024
	global_load_dwordx2 v[94:95], v[100:101], off offset:1152
	global_load_dwordx2 v[96:97], v[100:101], off offset:1280
	global_load_dwordx2 v[98:99], v[100:101], off offset:1408
	s_add_i32 s43, s43, 1
	v_readlane_b32 s4, v250, 2
	s_lshl_b32 s5, s43, 8
	s_add_i32 s5, s5, s4
	s_cmp_lt_u32 s5, 0xb00
	s_cselect_b64 s[38:39], -1, 0
	s_lshl_b32 s5, s43, 5
	s_lshr_b32 s48, s4, 3
	s_add_i32 s5, s5, s48
	s_and_b32 s4, s4, 7
	s_lshl_b32 s4, s4, 3
	s_cmp_ge_u32 s5, 0xb0
	s_cselect_b32 s48, 0xb0, 0
	s_cselect_b32 s45, 4, 0
	s_sub_i32 s5, s5, s48
	s_add_i32 s45, s45, s4
	s_and_b32 s4, s5, 3
	s_add_i32 s45, s45, s4
	s_lshr_b32 s44, s5, 2

.LBB0_798:
	s_lshl_b32 s51, s36, 15
	s_lshl_b32 s4, s33, 11
	s_add_u32 s4, s14, s4
	s_addc_u32 s5, s15, 0
	s_mov_b64 s[36:37], s[4:5]
	v_pk_mul_f32 v[146:147], v[150:151], v[146:147]
	v_lshl_add_u64 v[152:153], s[36:37], 0, v[80:81]
	v_mov_b32_e32 v170, v84
	v_mov_b32_e32 v171, v85
	s_add_u32 s36, s4, 0x80
	s_addc_u32 s37, s5, 0
	v_pk_mul_f32 v[144:145], v[148:149], v[144:145]
	v_lshl_add_u64 v[152:153], s[36:37], 0, v[80:81]
	v_mov_b32_e32 v164, v86
	v_mov_b32_e32 v165, v87
	s_add_u32 s36, s4, 0x100
	s_addc_u32 s37, s5, 0
	s_mul_i32 s33, s33, 0x2c0000
	v_lshl_add_u64 v[152:153], s[36:37], 0, v[80:81]
	v_mov_b32_e32 v162, v88
	v_mov_b32_e32 v163, v89
	s_add_u32 s36, s4, 0x180
	s_addc_u32 s37, s5, 0
	v_pk_mul_f32 v[138:139], v[142:143], v[138:139]
	v_lshl_add_u64 v[152:153], s[36:37], 0, v[80:81]
	v_mov_b32_e32 v160, v90
	v_mov_b32_e32 v161, v91
	s_add_u32 s36, s4, 0x400
	s_addc_u32 s37, s5, 0
	v_pk_mul_f32 v[136:137], v[140:141], v[136:137]
	v_lshl_add_u64 v[152:153], s[36:37], 0, v[80:81]
	s_add_u32 s36, s4, 0x480
	s_addc_u32 s37, s5, 0
	v_mov_b32_e32 v158, v92
	v_mov_b32_e32 v159, v93
	v_pk_mul_f32 v[130:131], v[134:135], v[130:131]
	v_lshl_add_u64 v[152:153], s[36:37], 0, v[80:81]
	s_add_u32 s36, s4, 0x500
	s_addc_u32 s37, s5, 0
	s_add_u32 s4, s4, 0x580
	v_mov_b32_e32 v156, v94
	v_mov_b32_e32 v157, v95
	s_addc_u32 s5, s5, 0
	v_lshl_add_u64 v[152:153], s[36:37], 0, v[80:81]
	v_mov_b32_e32 v154, v96
	v_mov_b32_e32 v155, v97
	s_add_i32 s33, s33, s51
	v_lshl_add_u64 v[152:153], s[4:5], 0, v[80:81]
	v_mov_b32_e32 v152, v98
	v_mov_b32_e32 v153, v99
	s_add_u32 s4, s20, s33
	s_addc_u32 s5, s68, 0
	s_mov_b64 s[36:37], s[4:5]
	v_pk_mul_f32 v[128:129], v[132:133], v[128:129]
	v_pk_mul_f32 v[122:123], v[126:127], v[122:123]
	v_pk_mul_f32 v[120:121], v[124:125], v[120:121]
	s_add_u32 s4, s4, 0x800
	s_addc_u32 s5, s5, 0
	v_pk_mul_f32 v[114:115], v[118:119], v[114:115]
	v_pk_mul_f32 v[112:113], v[116:117], v[112:113]
	v_pk_mul_f32 v[106:107], v[110:111], v[106:107]
	v_pk_mul_f32 v[104:105], v[108:109], v[104:105]
	v_pk_mul_f32 v[74:75], v[78:79], v[74:75]
	v_pk_mul_f32 v[72:73], v[76:77], v[72:73]
	v_pk_mul_f32 v[66:67], v[70:71], v[66:67]
	v_pk_mul_f32 v[64:65], v[68:69], v[64:65]
	v_pk_mul_f32 v[58:59], v[62:63], v[58:59]
	v_pk_mul_f32 v[56:57], v[60:61], v[56:57]
	v_pk_mul_f32 v[50:51], v[54:55], v[50:51]
	v_pk_mul_f32 v[48:49], v[52:53], v[48:49]
	v_pk_mul_f32 v[42:43], v[46:47], v[42:43]
	v_pk_mul_f32 v[40:41], v[44:45], v[40:41]
	v_pk_mul_f32 v[34:35], v[38:39], v[34:35]
	v_pk_mul_f32 v[32:33], v[36:37], v[32:33]
	v_pk_mul_f32 v[26:27], v[30:31], v[26:27]
	v_pk_mul_f32 v[24:25], v[28:29], v[24:25]
	v_pk_mul_f32 v[18:19], v[22:23], v[18:19]
	v_pk_mul_f32 v[16:17], v[20:21], v[16:17]
	v_pk_mul_f32 v[10:11], v[14:15], v[10:11]
	v_pk_mul_f32 v[8:9], v[12:13], v[8:9]
	v_pk_mul_f32 v[2:3], v[6:7], v[2:3]
	v_pk_mul_f32 v[0:1], v[4:5], v[0:1]
	s_and_b64 vcc, exec, s[2:3]
	s_cbranch_vccz .Lab_p5
	s_barrier
.Lab_p5:
	s_nop 0
	v_cvt_f32_u32_e32 v171, v171
	v_cvt_f32_u32_e32 v170, v170
	v_fmac_f32_e32 v170, 0x4f800000, v171
	v_fmamk_f32 v170, v170, 0x30000000, v234
	v_rsq_f32_e32 v178, v170
	s_nop 0
	v_mul_f32_e32 v174, 0xbfb8aa3b, v178
	v_pk_mul_f32 v[172:173], v[150:151], v[174:175] op_sel_hi:[1,0]
	v_pk_mul_f32 v[170:171], v[148:149], v[174:175] op_sel_hi:[1,0]
	v_pk_mul_f32 v[176:177], v[142:143], v[174:175] op_sel_hi:[1,0]
	v_pk_mul_f32 v[174:175], v[140:141], v[174:175] op_sel_hi:[1,0]
	v_mul_f32_e32 v178, v178, v178
	v_pk_mul_f32 v[180:181], v[146:147], v[178:179] op_sel_hi:[1,0]
	v_exp_f32_e32 v170, v170
	v_exp_f32_e32 v174, v174
	v_exp_f32_e32 v171, v171
	v_exp_f32_e32 v175, v175
	v_exp_f32_e32 v172, v172
	v_exp_f32_e32 v176, v176
	v_exp_f32_e32 v173, v173
	v_exp_f32_e32 v177, v177
	v_pk_mul_f32 v[182:183], v[144:145], v[178:179] op_sel_hi:[1,0]
	v_pk_add_f32 v[144:145], v[170:171], 1.0 op_sel_hi:[1,0]
	v_pk_add_f32 v[146:147], v[172:173], 1.0 op_sel_hi:[1,0]
	v_pk_add_f32 v[150:151], v[176:177], 1.0 op_sel_hi:[1,0]
	v_pk_add_f32 v[148:149], v[174:175], 1.0 op_sel_hi:[1,0]
	v_pk_mul_f32 v[138:139], v[138:139], v[178:179] op_sel_hi:[1,0]
	v_pk_mul_f32 v[136:137], v[136:137], v[178:179] op_sel_hi:[1,0]
	v_rcp_f32_e32 v144, v144
	v_rcp_f32_e32 v148, v148
	v_rcp_f32_e32 v145, v145
	v_rcp_f32_e32 v149, v149
	v_rcp_f32_e32 v146, v146
	v_rcp_f32_e32 v150, v150
	v_rcp_f32_e32 v147, v147
	v_rcp_f32_e32 v151, v151
	s_nop 0
	v_pk_mul_f32 v[140:141], v[180:181], v[146:147]
	v_pk_mul_f32 v[142:143], v[182:183], v[144:145]
	v_pk_mul_f32 v[144:145], v[138:139], v[150:151]
	v_pk_mul_f32 v[138:139], v[136:137], v[148:149]
	v_cvt_pk_bf16_f32 v136, v142, v143
	v_cvt_pk_bf16_f32 v137, v140, v141
	v_cvt_pk_bf16_f32 v138, v138, v139
	v_cvt_pk_bf16_f32 v139, v144, v145
	v_lshl_add_u64 v[140:141], s[36:37], 0, v[82:83]
	global_store_dwordx4 v[140:141], v[136:139], off nt
	s_nop 0
	s_nop 0
	v_cvt_f32_u32_e32 v136, v165
	v_cvt_f32_u32_e32 v137, v164
	v_fmac_f32_e32 v137, 0x4f800000, v136
	v_fmamk_f32 v136, v137, 0x30000000, v234
	v_rsq_f32_e32 v144, v136
	s_nop 0
	v_mul_f32_e32 v140, 0xbfb8aa3b, v144
	v_pk_mul_f32 v[138:139], v[134:135], v[140:141] op_sel_hi:[1,0]
	v_pk_mul_f32 v[136:137], v[132:133], v[140:141] op_sel_hi:[1,0]
	v_pk_mul_f32 v[142:143], v[126:127], v[140:141] op_sel_hi:[1,0]
	v_pk_mul_f32 v[140:141], v[124:125], v[140:141] op_sel_hi:[1,0]
	v_mul_f32_e32 v144, v144, v144
	v_pk_mul_f32 v[146:147], v[130:131], v[144:145] op_sel_hi:[1,0]
	v_exp_f32_e32 v136, v136
	v_exp_f32_e32 v140, v140
	v_exp_f32_e32 v137, v137
	v_exp_f32_e32 v141, v141
	v_exp_f32_e32 v138, v138
	v_exp_f32_e32 v142, v142
	v_exp_f32_e32 v139, v139
	v_exp_f32_e32 v143, v143
	v_pk_mul_f32 v[148:149], v[128:129], v[144:145] op_sel_hi:[1,0]
	v_pk_add_f32 v[128:129], v[136:137], 1.0 op_sel_hi:[1,0]
	v_pk_add_f32 v[130:131], v[138:139], 1.0 op_sel_hi:[1,0]
	v_pk_add_f32 v[134:135], v[142:143], 1.0 op_sel_hi:[1,0]
	v_pk_add_f32 v[132:133], v[140:141], 1.0 op_sel_hi:[1,0]
	v_pk_mul_f32 v[122:123], v[122:123], v[144:145] op_sel_hi:[1,0]
	v_pk_mul_f32 v[120:121], v[120:121], v[144:145] op_sel_hi:[1,0]
	v_rcp_f32_e32 v128, v128
	v_rcp_f32_e32 v132, v132
	v_rcp_f32_e32 v129, v129
	v_rcp_f32_e32 v133, v133
	v_rcp_f32_e32 v130, v130
	v_rcp_f32_e32 v134, v134
	v_rcp_f32_e32 v131, v131
	v_rcp_f32_e32 v135, v135
	s_nop 0
	v_pk_mul_f32 v[124:125], v[146:147], v[130:131]
	v_pk_mul_f32 v[126:127], v[148:149], v[128:129]
	v_pk_mul_f32 v[128:129], v[122:123], v[134:135]
	v_pk_mul_f32 v[122:123], v[120:121], v[132:133]
	v_cvt_pk_bf16_f32 v120, v126, v127
	v_cvt_pk_bf16_f32 v121, v124, v125
	v_cvt_pk_bf16_f32 v122, v122, v123
	v_cvt_pk_bf16_f32 v123, v128, v129
	v_lshl_add_u64 v[124:125], s[4:5], 0, v[82:83]
	global_store_dwordx4 v[124:125], v[120:123], off nt
	s_or_b32 s4, s33, 0x1000
	s_add_u32 s4, s20, s4
	s_nop 0
	v_cvt_f32_u32_e32 v120, v163
	v_cvt_f32_u32_e32 v121, v162
	s_addc_u32 s5, s68, 0
	v_fmac_f32_e32 v121, 0x4f800000, v120
	v_fmamk_f32 v120, v121, 0x30000000, v234
	v_rsq_f32_e32 v128, v120
	s_nop 0
	v_mul_f32_e32 v124, 0xbfb8aa3b, v128
	v_pk_mul_f32 v[122:123], v[118:119], v[124:125] op_sel_hi:[1,0]
	v_pk_mul_f32 v[120:121], v[116:117], v[124:125] op_sel_hi:[1,0]
	v_pk_mul_f32 v[126:127], v[110:111], v[124:125] op_sel_hi:[1,0]
	v_pk_mul_f32 v[124:125], v[108:109], v[124:125] op_sel_hi:[1,0]
	v_mul_f32_e32 v128, v128, v128
	v_pk_mul_f32 v[130:131], v[114:115], v[128:129] op_sel_hi:[1,0]
	v_exp_f32_e32 v120, v120
	v_exp_f32_e32 v124, v124
	v_exp_f32_e32 v121, v121
	v_exp_f32_e32 v125, v125
	v_exp_f32_e32 v122, v122
	v_exp_f32_e32 v126, v126
	v_exp_f32_e32 v123, v123
	v_exp_f32_e32 v127, v127
	v_pk_mul_f32 v[132:133], v[112:113], v[128:129] op_sel_hi:[1,0]
	v_pk_add_f32 v[112:113], v[120:121], 1.0 op_sel_hi:[1,0]
	v_pk_add_f32 v[114:115], v[122:123], 1.0 op_sel_hi:[1,0]
	v_pk_add_f32 v[118:119], v[126:127], 1.0 op_sel_hi:[1,0]
	v_pk_add_f32 v[116:117], v[124:125], 1.0 op_sel_hi:[1,0]
	v_pk_mul_f32 v[106:107], v[106:107], v[128:129] op_sel_hi:[1,0]
	v_pk_mul_f32 v[104:105], v[104:105], v[128:129] op_sel_hi:[1,0]
	v_rcp_f32_e32 v112, v112
	v_rcp_f32_e32 v116, v116
	v_rcp_f32_e32 v113, v113
	v_rcp_f32_e32 v117, v117
	v_rcp_f32_e32 v114, v114
	v_rcp_f32_e32 v118, v118
	v_rcp_f32_e32 v115, v115
	v_rcp_f32_e32 v119, v119
	s_nop 0
	v_pk_mul_f32 v[108:109], v[130:131], v[114:115]
	v_pk_mul_f32 v[110:111], v[132:133], v[112:113]
	v_pk_mul_f32 v[112:113], v[106:107], v[118:119]
	v_pk_mul_f32 v[106:107], v[104:105], v[116:117]
	v_cvt_pk_bf16_f32 v104, v110, v111
	v_cvt_pk_bf16_f32 v105, v108, v109
	v_cvt_pk_bf16_f32 v106, v106, v107
	v_cvt_pk_bf16_f32 v107, v112, v113
	v_lshl_add_u64 v[108:109], s[4:5], 0, v[82:83]
	global_store_dwordx4 v[108:109], v[104:107], off nt
	s_or_b32 s4, s33, 0x1800
	s_add_u32 s4, s20, s4
	s_nop 0
	v_cvt_f32_u32_e32 v104, v161
	v_cvt_f32_u32_e32 v105, v160
	s_addc_u32 s5, s68, 0
	v_fmac_f32_e32 v105, 0x4f800000, v104
	v_fmamk_f32 v104, v105, 0x30000000, v234
	v_rsq_f32_e32 v112, v104
	s_nop 0
	v_mul_f32_e32 v108, 0xbfb8aa3b, v112
	v_pk_mul_f32 v[106:107], v[78:79], v[108:109] op_sel_hi:[1,0]
	v_pk_mul_f32 v[104:105], v[76:77], v[108:109] op_sel_hi:[1,0]
	v_pk_mul_f32 v[110:111], v[70:71], v[108:109] op_sel_hi:[1,0]
	v_pk_mul_f32 v[108:109], v[68:69], v[108:109] op_sel_hi:[1,0]
	v_mul_f32_e32 v112, v112, v112
	v_pk_mul_f32 v[114:115], v[74:75], v[112:113] op_sel_hi:[1,0]
	v_exp_f32_e32 v104, v104
	v_exp_f32_e32 v108, v108
	v_exp_f32_e32 v105, v105
	v_exp_f32_e32 v109, v109
	v_exp_f32_e32 v106, v106
	v_exp_f32_e32 v110, v110
	v_exp_f32_e32 v107, v107
	v_exp_f32_e32 v111, v111
	v_pk_mul_f32 v[116:117], v[72:73], v[112:113] op_sel_hi:[1,0]
	v_pk_add_f32 v[72:73], v[104:105], 1.0 op_sel_hi:[1,0]
	v_pk_add_f32 v[74:75], v[106:107], 1.0 op_sel_hi:[1,0]
	v_pk_add_f32 v[78:79], v[110:111], 1.0 op_sel_hi:[1,0]
	v_pk_add_f32 v[76:77], v[108:109], 1.0 op_sel_hi:[1,0]
	v_pk_mul_f32 v[66:67], v[66:67], v[112:113] op_sel_hi:[1,0]
	v_pk_mul_f32 v[64:65], v[64:65], v[112:113] op_sel_hi:[1,0]
	v_rcp_f32_e32 v72, v72
	v_rcp_f32_e32 v76, v76
	v_rcp_f32_e32 v73, v73
	v_rcp_f32_e32 v77, v77
	v_rcp_f32_e32 v74, v74
	v_rcp_f32_e32 v78, v78
	v_rcp_f32_e32 v75, v75
	v_rcp_f32_e32 v79, v79
	s_nop 0
	v_pk_mul_f32 v[68:69], v[114:115], v[74:75]
	v_pk_mul_f32 v[70:71], v[116:117], v[72:73]
	v_pk_mul_f32 v[72:73], v[66:67], v[78:79]
	v_pk_mul_f32 v[66:67], v[64:65], v[76:77]
	v_cvt_pk_bf16_f32 v64, v70, v71
	v_cvt_pk_bf16_f32 v65, v68, v69
	v_cvt_pk_bf16_f32 v66, v66, v67
	v_cvt_pk_bf16_f32 v67, v72, v73
	v_lshl_add_u64 v[68:69], s[4:5], 0, v[82:83]
	global_store_dwordx4 v[68:69], v[64:67], off nt
	s_add_i32 s4, s33, 0x160000
	s_add_u32 s4, s20, s4
	s_nop 0
	v_cvt_f32_u32_e32 v64, v159
	v_cvt_f32_u32_e32 v65, v158
	s_addc_u32 s5, s68, 0
	v_fmac_f32_e32 v65, 0x4f800000, v64
	v_fmamk_f32 v64, v65, 0x30000000, v234
	v_rsq_f32_e32 v72, v64
	s_nop 0
	v_mul_f32_e32 v68, 0xbfb8aa3b, v72
	v_pk_mul_f32 v[66:67], v[62:63], v[68:69] op_sel_hi:[1,0]
	v_pk_mul_f32 v[64:65], v[60:61], v[68:69] op_sel_hi:[1,0]
	v_pk_mul_f32 v[70:71], v[54:55], v[68:69] op_sel_hi:[1,0]
	v_pk_mul_f32 v[68:69], v[52:53], v[68:69] op_sel_hi:[1,0]
	v_mul_f32_e32 v72, v72, v72
	v_pk_mul_f32 v[74:75], v[58:59], v[72:73] op_sel_hi:[1,0]
	v_exp_f32_e32 v64, v64
	v_exp_f32_e32 v68, v68
	v_exp_f32_e32 v65, v65
	v_exp_f32_e32 v69, v69
	v_exp_f32_e32 v66, v66
	v_exp_f32_e32 v70, v70
	v_exp_f32_e32 v67, v67
	v_exp_f32_e32 v71, v71
	v_pk_mul_f32 v[76:77], v[56:57], v[72:73] op_sel_hi:[1,0]
	v_pk_add_f32 v[56:57], v[64:65], 1.0 op_sel_hi:[1,0]
	v_pk_add_f32 v[58:59], v[66:67], 1.0 op_sel_hi:[1,0]
	v_pk_add_f32 v[62:63], v[70:71], 1.0 op_sel_hi:[1,0]
	v_pk_add_f32 v[60:61], v[68:69], 1.0 op_sel_hi:[1,0]
	v_pk_mul_f32 v[50:51], v[50:51], v[72:73] op_sel_hi:[1,0]
	v_pk_mul_f32 v[48:49], v[48:49], v[72:73] op_sel_hi:[1,0]
	v_rcp_f32_e32 v56, v56
	v_rcp_f32_e32 v60, v60
	v_rcp_f32_e32 v57, v57
	v_rcp_f32_e32 v61, v61
	v_rcp_f32_e32 v58, v58
	v_rcp_f32_e32 v62, v62
	v_rcp_f32_e32 v59, v59
	v_rcp_f32_e32 v63, v63
	s_nop 0
	v_pk_mul_f32 v[52:53], v[74:75], v[58:59]
	v_pk_mul_f32 v[54:55], v[76:77], v[56:57]
	v_pk_mul_f32 v[56:57], v[50:51], v[62:63]
	v_pk_mul_f32 v[50:51], v[48:49], v[60:61]
	v_cvt_pk_bf16_f32 v48, v54, v55
	v_cvt_pk_bf16_f32 v49, v52, v53
	v_cvt_pk_bf16_f32 v50, v50, v51
	v_cvt_pk_bf16_f32 v51, v56, v57
	v_lshl_add_u64 v[52:53], s[4:5], 0, v[82:83]
	global_store_dwordx4 v[52:53], v[48:51], off nt
	s_add_i32 s4, s33, 0x160800
	s_add_u32 s4, s20, s4
	s_nop 0
	v_cvt_f32_u32_e32 v48, v157
	v_cvt_f32_u32_e32 v49, v156
	s_addc_u32 s5, s68, 0
	v_fmac_f32_e32 v49, 0x4f800000, v48
	v_fmamk_f32 v48, v49, 0x30000000, v234
	v_rsq_f32_e32 v56, v48
	s_nop 0
	v_mul_f32_e32 v52, 0xbfb8aa3b, v56
	v_pk_mul_f32 v[50:51], v[46:47], v[52:53] op_sel_hi:[1,0]
	v_pk_mul_f32 v[48:49], v[44:45], v[52:53] op_sel_hi:[1,0]
	v_pk_mul_f32 v[54:55], v[38:39], v[52:53] op_sel_hi:[1,0]
	v_pk_mul_f32 v[52:53], v[36:37], v[52:53] op_sel_hi:[1,0]
	v_mul_f32_e32 v56, v56, v56
	v_pk_mul_f32 v[58:59], v[42:43], v[56:57] op_sel_hi:[1,0]
	v_exp_f32_e32 v48, v48
	v_exp_f32_e32 v52, v52
	v_exp_f32_e32 v49, v49
	v_exp_f32_e32 v53, v53
	v_exp_f32_e32 v50, v50
	v_exp_f32_e32 v54, v54
	v_exp_f32_e32 v51, v51
	v_exp_f32_e32 v55, v55
	v_pk_mul_f32 v[60:61], v[40:41], v[56:57] op_sel_hi:[1,0]
	v_pk_add_f32 v[40:41], v[48:49], 1.0 op_sel_hi:[1,0]
	v_pk_add_f32 v[42:43], v[50:51], 1.0 op_sel_hi:[1,0]
	v_pk_add_f32 v[46:47], v[54:55], 1.0 op_sel_hi:[1,0]
	v_pk_add_f32 v[44:45], v[52:53], 1.0 op_sel_hi:[1,0]
	v_pk_mul_f32 v[34:35], v[34:35], v[56:57] op_sel_hi:[1,0]
	v_pk_mul_f32 v[32:33], v[32:33], v[56:57] op_sel_hi:[1,0]
	v_rcp_f32_e32 v40, v40
	v_rcp_f32_e32 v44, v44
	v_rcp_f32_e32 v41, v41
	v_rcp_f32_e32 v45, v45
	v_rcp_f32_e32 v42, v42
	v_rcp_f32_e32 v46, v46
	v_rcp_f32_e32 v43, v43
	v_rcp_f32_e32 v47, v47
	s_nop 0
	v_pk_mul_f32 v[36:37], v[58:59], v[42:43]
	v_pk_mul_f32 v[38:39], v[60:61], v[40:41]
	v_pk_mul_f32 v[40:41], v[34:35], v[46:47]
	v_pk_mul_f32 v[34:35], v[32:33], v[44:45]
	v_cvt_pk_bf16_f32 v32, v38, v39
	v_cvt_pk_bf16_f32 v33, v36, v37
	v_cvt_pk_bf16_f32 v34, v34, v35
	v_cvt_pk_bf16_f32 v35, v40, v41
	v_lshl_add_u64 v[36:37], s[4:5], 0, v[82:83]
	global_store_dwordx4 v[36:37], v[32:35], off nt
	s_add_i32 s4, s33, 0x161000
	s_add_u32 s4, s20, s4
	s_nop 0
	v_cvt_f32_u32_e32 v32, v155
	v_cvt_f32_u32_e32 v33, v154
	s_addc_u32 s5, s68, 0
	s_add_i32 s33, s33, 0x161800
	v_fmac_f32_e32 v33, 0x4f800000, v32
	v_fmamk_f32 v32, v33, 0x30000000, v234
	v_rsq_f32_e32 v40, v32
	s_nop 0
	v_mul_f32_e32 v36, 0xbfb8aa3b, v40
	v_pk_mul_f32 v[34:35], v[30:31], v[36:37] op_sel_hi:[1,0]
	v_pk_mul_f32 v[32:33], v[28:29], v[36:37] op_sel_hi:[1,0]
	v_pk_mul_f32 v[38:39], v[22:23], v[36:37] op_sel_hi:[1,0]
	v_pk_mul_f32 v[36:37], v[20:21], v[36:37] op_sel_hi:[1,0]
	v_mul_f32_e32 v40, v40, v40
	v_pk_mul_f32 v[42:43], v[26:27], v[40:41] op_sel_hi:[1,0]
	v_exp_f32_e32 v32, v32
	v_exp_f32_e32 v36, v36
	v_exp_f32_e32 v33, v33
	v_exp_f32_e32 v37, v37
	v_exp_f32_e32 v34, v34
	v_exp_f32_e32 v38, v38
	v_exp_f32_e32 v35, v35
	v_exp_f32_e32 v39, v39
	v_pk_mul_f32 v[44:45], v[24:25], v[40:41] op_sel_hi:[1,0]
	v_pk_add_f32 v[24:25], v[32:33], 1.0 op_sel_hi:[1,0]
	v_pk_add_f32 v[26:27], v[34:35], 1.0 op_sel_hi:[1,0]
	v_pk_add_f32 v[30:31], v[38:39], 1.0 op_sel_hi:[1,0]
	v_pk_add_f32 v[28:29], v[36:37], 1.0 op_sel_hi:[1,0]
	v_pk_mul_f32 v[18:19], v[18:19], v[40:41] op_sel_hi:[1,0]
	v_pk_mul_f32 v[16:17], v[16:17], v[40:41] op_sel_hi:[1,0]
	v_rcp_f32_e32 v24, v24
	v_rcp_f32_e32 v28, v28
	v_rcp_f32_e32 v25, v25
	v_rcp_f32_e32 v29, v29
	v_rcp_f32_e32 v26, v26
	v_rcp_f32_e32 v30, v30
	v_rcp_f32_e32 v27, v27
	v_rcp_f32_e32 v31, v31
	s_nop 0
	v_pk_mul_f32 v[20:21], v[42:43], v[26:27]
	v_pk_mul_f32 v[22:23], v[44:45], v[24:25]
	v_pk_mul_f32 v[24:25], v[18:19], v[30:31]
	v_pk_mul_f32 v[18:19], v[16:17], v[28:29]
	v_cvt_pk_bf16_f32 v16, v22, v23
	v_cvt_pk_bf16_f32 v17, v20, v21
	v_cvt_pk_bf16_f32 v18, v18, v19
	v_cvt_pk_bf16_f32 v19, v24, v25
	v_lshl_add_u64 v[20:21], s[4:5], 0, v[82:83]
	global_store_dwordx4 v[20:21], v[16:19], off nt
	s_add_u32 s4, s20, s33
	s_addc_u32 s5, s68, 0
	s_nop 0
	v_cvt_f32_u32_e32 v16, v153
	v_cvt_f32_u32_e32 v17, v152
	s_andn2_b64 vcc, exec, s[38:39]
	v_fmac_f32_e32 v17, 0x4f800000, v16
	v_fmamk_f32 v16, v17, 0x30000000, v234
	v_rsq_f32_e32 v24, v16
	s_nop 0
	v_mul_f32_e32 v20, 0xbfb8aa3b, v24
	v_pk_mul_f32 v[18:19], v[14:15], v[20:21] op_sel_hi:[1,0]
	v_pk_mul_f32 v[16:17], v[12:13], v[20:21] op_sel_hi:[1,0]
	v_pk_mul_f32 v[22:23], v[6:7], v[20:21] op_sel_hi:[1,0]
	v_pk_mul_f32 v[20:21], v[4:5], v[20:21] op_sel_hi:[1,0]
	v_mul_f32_e32 v24, v24, v24
	v_pk_mul_f32 v[26:27], v[10:11], v[24:25] op_sel_hi:[1,0]
	v_exp_f32_e32 v16, v16
	v_exp_f32_e32 v20, v20
	v_exp_f32_e32 v17, v17
	v_exp_f32_e32 v21, v21
	v_exp_f32_e32 v18, v18
	v_exp_f32_e32 v22, v22
	v_exp_f32_e32 v19, v19
	v_exp_f32_e32 v23, v23
	v_pk_mul_f32 v[28:29], v[8:9], v[24:25] op_sel_hi:[1,0]
	v_pk_add_f32 v[8:9], v[16:17], 1.0 op_sel_hi:[1,0]
	v_pk_add_f32 v[10:11], v[18:19], 1.0 op_sel_hi:[1,0]
	v_pk_add_f32 v[14:15], v[22:23], 1.0 op_sel_hi:[1,0]
	v_pk_add_f32 v[12:13], v[20:21], 1.0 op_sel_hi:[1,0]
	v_pk_mul_f32 v[2:3], v[2:3], v[24:25] op_sel_hi:[1,0]
	v_pk_mul_f32 v[0:1], v[0:1], v[24:25] op_sel_hi:[1,0]
	v_rcp_f32_e32 v8, v8
	v_rcp_f32_e32 v12, v12
	v_rcp_f32_e32 v9, v9
	v_rcp_f32_e32 v13, v13
	v_rcp_f32_e32 v10, v10
	v_rcp_f32_e32 v14, v14
	v_rcp_f32_e32 v11, v11
	v_rcp_f32_e32 v15, v15
	s_nop 0
	v_pk_mul_f32 v[4:5], v[26:27], v[10:11]
	v_pk_mul_f32 v[6:7], v[28:29], v[8:9]
	v_pk_mul_f32 v[8:9], v[2:3], v[14:15]
	v_pk_mul_f32 v[2:3], v[0:1], v[12:13]
	v_cvt_pk_bf16_f32 v0, v6, v7
	v_cvt_pk_bf16_f32 v1, v4, v5
	v_cvt_pk_bf16_f32 v2, v2, v3
	v_cvt_pk_bf16_f32 v3, v8, v9
	v_lshl_add_u64 v[4:5], s[4:5], 0, v[82:83]
	s_mov_b64 s[4:5], -1
	global_store_dwordx4 v[4:5], v[0:3], off nt
	s_cbranch_vccnz .LBB0_791
	s_mov_b32 s101, 0
	s_andn2_b64 vcc, exec, s[0:1]
	s_cbranch_vccnz .LBB0_790
	s_mov_b32 s101, 1
	s_branch .LBB0_790
